# nt (streaming) hint on the SwiGLU H stores and the EpiResid residual-stream stores
# speedup vs baseline: 1.0045x; 1.0045x over previous
; #define PG8_LAS __attribute__((address_space(3)))
; __device__ __forceinline__ unsigned cvt_pk_bf16(float lo, float hi) { unsigned r; asm volatile("v_cvt_pk_bf16_f32 %0, %1, %2" : "=v"(r) : "v"(lo), "v"(hi)); return r; }
; __device__ __forceinline__ float silu_f(float g) { return g * __builtin_amdgcn_rcpf(1.0f + __expf(-g)); }
;     __device__ __forceinline__ void operator()(const f32x4 (&acc)[2][2][4][2], const Unit& u, int wr, int wc, int fr, int fq, PG8_LAS unsigned char*) const {
;         const int row0 = u.pm * BM + wr * 64 + fr, col0 = u.pn * HALF + wc * 32 + 8 * fq;
; #pragma unroll
;         for (int ai = 0; ai < 2; ++ai)
; #pragma unroll
;             for (int m = 0; m < 4; ++m) { bf16_t* rowp = H + (size_t)(row0 + ai * HALF + m * 16) * ldh + col0;
;                 const f32x4 g0 = acc[ai][0][m][0], g1 = acc[ai][0][m][1], u0 = acc[ai][1][m][0], u1 = acc[ai][1][m][1];
;                 u32x4 w;
;                 w.x = cvt_pk_bf16(silu_f(g0[0]) * u0[0], silu_f(g0[1]) * u0[1]); w.y = cvt_pk_bf16(silu_f(g0[2]) * u0[2], silu_f(g0[3]) * u0[3]);
;                 w.z = cvt_pk_bf16(silu_f(g1[0]) * u1[0], silu_f(g1[1]) * u1[1]); w.w = cvt_pk_bf16(silu_f(g1[2]) * u1[2], silu_f(g1[3]) * u1[3]);
;                 *(u32x4*)rowp = w; }
.LBB0_154:
	v_lshl_or_b32 v162, s89, 7, v166
	v_lshl_add_u32 v176, s96, 8, v164
	v_ashrrev_i32_e32 v163, 31, v162
	v_mov_b64_e32 v[160:161], s[92:93]
	v_lshlrev_b64 v[162:163], 1, v[162:163]
	s_mov_b64 s[46:47], -1
	s_mov_b32 s100, 0xbfb8aa3b
	s_mov_b32 s101, 0xbfb8aa3b
	v_mov_b32_e32 v184, v176
	v_mad_i64_i32 v[184:185], s[38:39], v184, s21, v[160:161]
	v_lshl_add_u64 v[184:185], v[184:185], 0, v[162:163]
	v_pk_mul_f32 v[180:181], v[128:129], s[100:101]
	v_pk_mul_f32 v[182:183], v[130:131], s[100:101]
	v_exp_f32_e32 v180, v180
	v_exp_f32_e32 v181, v181
	v_exp_f32_e32 v182, v182
	v_exp_f32_e32 v183, v183
	v_pk_add_f32 v[180:181], v[180:181], 1.0 op_sel_hi:[1,0]
	v_pk_add_f32 v[182:183], v[182:183], 1.0 op_sel_hi:[1,0]
	v_rcp_f32_e32 v180, v180
	v_rcp_f32_e32 v181, v181
	v_rcp_f32_e32 v182, v182
	v_rcp_f32_e32 v183, v183
	v_pk_mul_f32 v[180:181], v[128:129], v[180:181]
	v_pk_mul_f32 v[182:183], v[130:131], v[182:183]
	v_pk_mul_f32 v[180:181], v[180:181], v[124:125]
	v_pk_mul_f32 v[182:183], v[182:183], v[126:127]
	v_cvt_pk_bf16_f32 v124, v180, v181
	v_cvt_pk_bf16_f32 v125, v182, v183
	v_pk_mul_f32 v[180:181], v[120:121], s[100:101]
	v_pk_mul_f32 v[182:183], v[122:123], s[100:101]
	v_exp_f32_e32 v180, v180
	v_exp_f32_e32 v181, v181
	v_exp_f32_e32 v182, v182
	v_exp_f32_e32 v183, v183
	v_pk_add_f32 v[180:181], v[180:181], 1.0 op_sel_hi:[1,0]
	v_pk_add_f32 v[182:183], v[182:183], 1.0 op_sel_hi:[1,0]
	v_rcp_f32_e32 v180, v180
	v_rcp_f32_e32 v181, v181
	v_rcp_f32_e32 v182, v182
	v_rcp_f32_e32 v183, v183
	v_pk_mul_f32 v[180:181], v[120:121], v[180:181]
	v_pk_mul_f32 v[182:183], v[122:123], v[182:183]
	v_pk_mul_f32 v[180:181], v[180:181], v[116:117]
	v_pk_mul_f32 v[182:183], v[182:183], v[118:119]
	v_cvt_pk_bf16_f32 v126, v180, v181
	v_cvt_pk_bf16_f32 v127, v182, v183
	global_store_dwordx4 v[184:185], v[124:127], off nt
	v_or_b32_e32 v186, 16, v176
	v_mad_i64_i32 v[186:187], s[38:39], v186, s21, v[160:161]
	v_lshl_add_u64 v[186:187], v[186:187], 0, v[162:163]
	v_pk_mul_f32 v[180:181], v[112:113], s[100:101]
	v_pk_mul_f32 v[182:183], v[114:115], s[100:101]
	v_exp_f32_e32 v180, v180
	v_exp_f32_e32 v181, v181
	v_exp_f32_e32 v182, v182
	v_exp_f32_e32 v183, v183
	v_pk_add_f32 v[180:181], v[180:181], 1.0 op_sel_hi:[1,0]
	v_pk_add_f32 v[182:183], v[182:183], 1.0 op_sel_hi:[1,0]
	v_rcp_f32_e32 v180, v180
	v_rcp_f32_e32 v181, v181
	v_rcp_f32_e32 v182, v182
	v_rcp_f32_e32 v183, v183
	v_pk_mul_f32 v[180:181], v[112:113], v[180:181]
	v_pk_mul_f32 v[182:183], v[114:115], v[182:183]
	v_pk_mul_f32 v[180:181], v[180:181], v[108:109]
	v_pk_mul_f32 v[182:183], v[182:183], v[110:111]
	v_cvt_pk_bf16_f32 v108, v180, v181
	v_cvt_pk_bf16_f32 v109, v182, v183
	v_pk_mul_f32 v[180:181], v[104:105], s[100:101]
	v_pk_mul_f32 v[182:183], v[106:107], s[100:101]
	v_exp_f32_e32 v180, v180
	v_exp_f32_e32 v181, v181
	v_exp_f32_e32 v182, v182
	v_exp_f32_e32 v183, v183
	v_pk_add_f32 v[180:181], v[180:181], 1.0 op_sel_hi:[1,0]
	v_pk_add_f32 v[182:183], v[182:183], 1.0 op_sel_hi:[1,0]
	v_rcp_f32_e32 v180, v180
	v_rcp_f32_e32 v181, v181
	v_rcp_f32_e32 v182, v182
	v_rcp_f32_e32 v183, v183
	v_pk_mul_f32 v[180:181], v[104:105], v[180:181]
	v_pk_mul_f32 v[182:183], v[106:107], v[182:183]
	v_pk_mul_f32 v[180:181], v[180:181], v[100:101]
	v_pk_mul_f32 v[182:183], v[182:183], v[102:103]
	v_cvt_pk_bf16_f32 v110, v180, v181
	v_cvt_pk_bf16_f32 v111, v182, v183
	global_store_dwordx4 v[186:187], v[108:111], off nt
	v_or_b32_e32 v184, 32, v176
	v_mad_i64_i32 v[184:185], s[38:39], v184, s21, v[160:161]
	v_lshl_add_u64 v[184:185], v[184:185], 0, v[162:163]
	v_pk_mul_f32 v[180:181], v[96:97], s[100:101]
	v_pk_mul_f32 v[182:183], v[98:99], s[100:101]
	v_exp_f32_e32 v180, v180
	v_exp_f32_e32 v181, v181
	v_exp_f32_e32 v182, v182
	v_exp_f32_e32 v183, v183
	v_pk_add_f32 v[180:181], v[180:181], 1.0 op_sel_hi:[1,0]
	v_pk_add_f32 v[182:183], v[182:183], 1.0 op_sel_hi:[1,0]
	v_rcp_f32_e32 v180, v180
	v_rcp_f32_e32 v181, v181
	v_rcp_f32_e32 v182, v182
	v_rcp_f32_e32 v183, v183
	v_pk_mul_f32 v[180:181], v[96:97], v[180:181]
	v_pk_mul_f32 v[182:183], v[98:99], v[182:183]
	v_pk_mul_f32 v[180:181], v[180:181], v[92:93]
	v_pk_mul_f32 v[182:183], v[182:183], v[94:95]
	v_cvt_pk_bf16_f32 v92, v180, v181
	v_cvt_pk_bf16_f32 v93, v182, v183
	v_pk_mul_f32 v[180:181], v[88:89], s[100:101]
	v_pk_mul_f32 v[182:183], v[90:91], s[100:101]
	v_exp_f32_e32 v180, v180
	v_exp_f32_e32 v181, v181
	v_exp_f32_e32 v182, v182
	v_exp_f32_e32 v183, v183
	v_pk_add_f32 v[180:181], v[180:181], 1.0 op_sel_hi:[1,0]
	v_pk_add_f32 v[182:183], v[182:183], 1.0 op_sel_hi:[1,0]
	v_rcp_f32_e32 v180, v180
	v_rcp_f32_e32 v181, v181
	v_rcp_f32_e32 v182, v182
	v_rcp_f32_e32 v183, v183
	v_pk_mul_f32 v[180:181], v[88:89], v[180:181]
	v_pk_mul_f32 v[182:183], v[90:91], v[182:183]
	v_pk_mul_f32 v[180:181], v[180:181], v[84:85]
	v_pk_mul_f32 v[182:183], v[182:183], v[86:87]
	v_cvt_pk_bf16_f32 v94, v180, v181
	v_cvt_pk_bf16_f32 v95, v182, v183
	global_store_dwordx4 v[184:185], v[92:95], off nt
	v_or_b32_e32 v186, 48, v176
	v_mad_i64_i32 v[186:187], s[38:39], v186, s21, v[160:161]
	v_lshl_add_u64 v[186:187], v[186:187], 0, v[162:163]
	v_pk_mul_f32 v[180:181], v[80:81], s[100:101]
	v_pk_mul_f32 v[182:183], v[82:83], s[100:101]
	v_exp_f32_e32 v180, v180
	v_exp_f32_e32 v181, v181
	v_exp_f32_e32 v182, v182
	v_exp_f32_e32 v183, v183
	v_pk_add_f32 v[180:181], v[180:181], 1.0 op_sel_hi:[1,0]
	v_pk_add_f32 v[182:183], v[182:183], 1.0 op_sel_hi:[1,0]
	v_rcp_f32_e32 v180, v180
	v_rcp_f32_e32 v181, v181
	v_rcp_f32_e32 v182, v182
	v_rcp_f32_e32 v183, v183
	v_pk_mul_f32 v[180:181], v[80:81], v[180:181]
	v_pk_mul_f32 v[182:183], v[82:83], v[182:183]
; __device__ __forceinline__ unsigned cvt_pk_bf16(float lo, float hi) { unsigned r; asm volatile("v_cvt_pk_bf16_f32 %0, %1, %2" : "=v"(r) : "v"(lo), "v"(hi)); return r; }
; __device__ __forceinline__ float silu_f(float g) { return g * __builtin_amdgcn_rcpf(1.0f + __expf(-g)); }
;     __device__ __forceinline__ void operator()(const f32x4 (&acc)[2][2][4][2], const Unit& u, int wr, int wc, int fr, int fq, PG8_LAS unsigned char*) const {
;     ...
;             for (int m = 0; m < 4; ++m) { bf16_t* rowp = H + (size_t)(row0 + ai * HALF + m * 16) * ldh + col0;
;                 const f32x4 g0 = acc[ai][0][m][0], g1 = acc[ai][0][m][1], u0 = acc[ai][1][m][0], u1 = acc[ai][1][m][1];
;                 u32x4 w;
;                 w.x = cvt_pk_bf16(silu_f(g0[0]) * u0[0], silu_f(g0[1]) * u0[1]); w.y = cvt_pk_bf16(silu_f(g0[2]) * u0[2], silu_f(g0[3]) * u0[3]);
;                 w.z = cvt_pk_bf16(silu_f(g1[0]) * u1[0], silu_f(g1[1]) * u1[1]); w.w = cvt_pk_bf16(silu_f(g1[2]) * u1[2], silu_f(g1[3]) * u1[3]);
;                 *(u32x4*)rowp = w; }
	v_pk_mul_f32 v[180:181], v[180:181], v[76:77]
	v_pk_mul_f32 v[182:183], v[182:183], v[78:79]
	v_cvt_pk_bf16_f32 v76, v180, v181
	v_cvt_pk_bf16_f32 v77, v182, v183
	v_pk_mul_f32 v[180:181], v[72:73], s[100:101]
	v_pk_mul_f32 v[182:183], v[74:75], s[100:101]
	v_exp_f32_e32 v180, v180
	v_exp_f32_e32 v181, v181
	v_exp_f32_e32 v182, v182
	v_exp_f32_e32 v183, v183
	v_pk_add_f32 v[180:181], v[180:181], 1.0 op_sel_hi:[1,0]
	v_pk_add_f32 v[182:183], v[182:183], 1.0 op_sel_hi:[1,0]
	v_rcp_f32_e32 v180, v180
	v_rcp_f32_e32 v181, v181
	v_rcp_f32_e32 v182, v182
	v_rcp_f32_e32 v183, v183
	v_pk_mul_f32 v[180:181], v[72:73], v[180:181]
	v_pk_mul_f32 v[182:183], v[74:75], v[182:183]
	v_pk_mul_f32 v[180:181], v[180:181], v[68:69]
	v_pk_mul_f32 v[182:183], v[182:183], v[70:71]
	v_cvt_pk_bf16_f32 v78, v180, v181
	v_cvt_pk_bf16_f32 v79, v182, v183
	global_store_dwordx4 v[186:187], v[76:79], off nt
	v_add_u32_e32 v184, 0x80, v176
	v_mad_i64_i32 v[184:185], s[38:39], v184, s21, v[160:161]
	v_lshl_add_u64 v[184:185], v[184:185], 0, v[162:163]
	v_pk_mul_f32 v[180:181], v[64:65], s[100:101]
	v_pk_mul_f32 v[182:183], v[66:67], s[100:101]
	v_exp_f32_e32 v180, v180
	v_exp_f32_e32 v181, v181
	v_exp_f32_e32 v182, v182
	v_exp_f32_e32 v183, v183
	v_pk_add_f32 v[180:181], v[180:181], 1.0 op_sel_hi:[1,0]
	v_pk_add_f32 v[182:183], v[182:183], 1.0 op_sel_hi:[1,0]
	v_rcp_f32_e32 v180, v180
	v_rcp_f32_e32 v181, v181
	v_rcp_f32_e32 v182, v182
	v_rcp_f32_e32 v183, v183
	v_pk_mul_f32 v[180:181], v[64:65], v[180:181]
	v_pk_mul_f32 v[182:183], v[66:67], v[182:183]
	v_pk_mul_f32 v[180:181], v[180:181], v[60:61]
	v_pk_mul_f32 v[182:183], v[182:183], v[62:63]
	v_cvt_pk_bf16_f32 v60, v180, v181
	v_cvt_pk_bf16_f32 v61, v182, v183
	v_pk_mul_f32 v[180:181], v[56:57], s[100:101]
	v_pk_mul_f32 v[182:183], v[58:59], s[100:101]
	v_exp_f32_e32 v180, v180
	v_exp_f32_e32 v181, v181
	v_exp_f32_e32 v182, v182
	v_exp_f32_e32 v183, v183
	v_pk_add_f32 v[180:181], v[180:181], 1.0 op_sel_hi:[1,0]
	v_pk_add_f32 v[182:183], v[182:183], 1.0 op_sel_hi:[1,0]
	v_rcp_f32_e32 v180, v180
	v_rcp_f32_e32 v181, v181
	v_rcp_f32_e32 v182, v182
	v_rcp_f32_e32 v183, v183
	v_pk_mul_f32 v[180:181], v[56:57], v[180:181]
	v_pk_mul_f32 v[182:183], v[58:59], v[182:183]
	v_pk_mul_f32 v[180:181], v[180:181], v[52:53]
	v_pk_mul_f32 v[182:183], v[182:183], v[54:55]
	v_cvt_pk_bf16_f32 v62, v180, v181
	v_cvt_pk_bf16_f32 v63, v182, v183
	global_store_dwordx4 v[184:185], v[60:63], off nt
	v_add_u32_e32 v186, 0x90, v176
	v_mad_i64_i32 v[186:187], s[38:39], v186, s21, v[160:161]
	v_lshl_add_u64 v[186:187], v[186:187], 0, v[162:163]
	v_pk_mul_f32 v[180:181], v[48:49], s[100:101]
	v_pk_mul_f32 v[182:183], v[50:51], s[100:101]
	v_exp_f32_e32 v180, v180
	v_exp_f32_e32 v181, v181
	v_exp_f32_e32 v182, v182
	v_exp_f32_e32 v183, v183
	v_pk_add_f32 v[180:181], v[180:181], 1.0 op_sel_hi:[1,0]
	v_pk_add_f32 v[182:183], v[182:183], 1.0 op_sel_hi:[1,0]
	v_rcp_f32_e32 v180, v180
	v_rcp_f32_e32 v181, v181
	v_rcp_f32_e32 v182, v182
	v_rcp_f32_e32 v183, v183
	v_pk_mul_f32 v[180:181], v[48:49], v[180:181]
	v_pk_mul_f32 v[182:183], v[50:51], v[182:183]
	v_pk_mul_f32 v[180:181], v[180:181], v[44:45]
	v_pk_mul_f32 v[182:183], v[182:183], v[46:47]
	v_cvt_pk_bf16_f32 v44, v180, v181
	v_cvt_pk_bf16_f32 v45, v182, v183
	v_pk_mul_f32 v[180:181], v[40:41], s[100:101]
	v_pk_mul_f32 v[182:183], v[42:43], s[100:101]
	v_exp_f32_e32 v180, v180
	v_exp_f32_e32 v181, v181
	v_exp_f32_e32 v182, v182
	v_exp_f32_e32 v183, v183
	v_pk_add_f32 v[180:181], v[180:181], 1.0 op_sel_hi:[1,0]
	v_pk_add_f32 v[182:183], v[182:183], 1.0 op_sel_hi:[1,0]
	v_rcp_f32_e32 v180, v180
; __device__ __forceinline__ unsigned cvt_pk_bf16(float lo, float hi) { unsigned r; asm volatile("v_cvt_pk_bf16_f32 %0, %1, %2" : "=v"(r) : "v"(lo), "v"(hi)); return r; }
; __device__ __forceinline__ float silu_f(float g) { return g * __builtin_amdgcn_rcpf(1.0f + __expf(-g)); }
;     __device__ __forceinline__ void operator()(const f32x4 (&acc)[2][2][4][2], const Unit& u, int wr, int wc, int fr, int fq, PG8_LAS unsigned char*) const {
;     ...
;             for (int m = 0; m < 4; ++m) { bf16_t* rowp = H + (size_t)(row0 + ai * HALF + m * 16) * ldh + col0;
;                 const f32x4 g0 = acc[ai][0][m][0], g1 = acc[ai][0][m][1], u0 = acc[ai][1][m][0], u1 = acc[ai][1][m][1];
;                 u32x4 w;
;                 w.x = cvt_pk_bf16(silu_f(g0[0]) * u0[0], silu_f(g0[1]) * u0[1]); w.y = cvt_pk_bf16(silu_f(g0[2]) * u0[2], silu_f(g0[3]) * u0[3]);
;                 w.z = cvt_pk_bf16(silu_f(g1[0]) * u1[0], silu_f(g1[1]) * u1[1]); w.w = cvt_pk_bf16(silu_f(g1[2]) * u1[2], silu_f(g1[3]) * u1[3]);
;                 *(u32x4*)rowp = w; }
; template <class Epi, class Sched, bool ALIGN_EPI = false, bool SP2 = false>
; __device__ __forceinline__ void gemm_phase(PG8_LAS unsigned char* lds, const Gemm g, const Sched& S, const Epi& E) {
;     ...
;         if (!has_next) break;
	v_rcp_f32_e32 v181, v181
	v_rcp_f32_e32 v182, v182
	v_rcp_f32_e32 v183, v183
	v_pk_mul_f32 v[180:181], v[40:41], v[180:181]
	v_pk_mul_f32 v[182:183], v[42:43], v[182:183]
	v_pk_mul_f32 v[180:181], v[180:181], v[36:37]
	v_pk_mul_f32 v[182:183], v[182:183], v[38:39]
	v_cvt_pk_bf16_f32 v46, v180, v181
	v_cvt_pk_bf16_f32 v47, v182, v183
	global_store_dwordx4 v[186:187], v[44:47], off nt
	v_add_u32_e32 v184, 0xa0, v176
	v_mad_i64_i32 v[184:185], s[38:39], v184, s21, v[160:161]
	v_lshl_add_u64 v[184:185], v[184:185], 0, v[162:163]
	v_pk_mul_f32 v[180:181], v[32:33], s[100:101]
	v_pk_mul_f32 v[182:183], v[34:35], s[100:101]
	v_exp_f32_e32 v180, v180
	v_exp_f32_e32 v181, v181
	v_exp_f32_e32 v182, v182
	v_exp_f32_e32 v183, v183
	v_pk_add_f32 v[180:181], v[180:181], 1.0 op_sel_hi:[1,0]
	v_pk_add_f32 v[182:183], v[182:183], 1.0 op_sel_hi:[1,0]
	v_rcp_f32_e32 v180, v180
	v_rcp_f32_e32 v181, v181
	v_rcp_f32_e32 v182, v182
	v_rcp_f32_e32 v183, v183
	v_pk_mul_f32 v[180:181], v[32:33], v[180:181]
	v_pk_mul_f32 v[182:183], v[34:35], v[182:183]
	v_pk_mul_f32 v[180:181], v[180:181], v[28:29]
	v_pk_mul_f32 v[182:183], v[182:183], v[30:31]
	v_cvt_pk_bf16_f32 v28, v180, v181
	v_cvt_pk_bf16_f32 v29, v182, v183
	v_pk_mul_f32 v[180:181], v[24:25], s[100:101]
	v_pk_mul_f32 v[182:183], v[26:27], s[100:101]
	v_exp_f32_e32 v180, v180
	v_exp_f32_e32 v181, v181
	v_exp_f32_e32 v182, v182
	v_exp_f32_e32 v183, v183
	v_pk_add_f32 v[180:181], v[180:181], 1.0 op_sel_hi:[1,0]
	v_pk_add_f32 v[182:183], v[182:183], 1.0 op_sel_hi:[1,0]
	v_rcp_f32_e32 v180, v180
	v_rcp_f32_e32 v181, v181
	v_rcp_f32_e32 v182, v182
	v_rcp_f32_e32 v183, v183
	v_pk_mul_f32 v[180:181], v[24:25], v[180:181]
	v_pk_mul_f32 v[182:183], v[26:27], v[182:183]
	v_pk_mul_f32 v[180:181], v[180:181], v[20:21]
	v_pk_mul_f32 v[182:183], v[182:183], v[22:23]
	v_cvt_pk_bf16_f32 v30, v180, v181
	v_cvt_pk_bf16_f32 v31, v182, v183
	global_store_dwordx4 v[184:185], v[28:31], off nt
	v_add_u32_e32 v186, 0xb0, v176
	v_mad_i64_i32 v[186:187], s[38:39], v186, s21, v[160:161]
	v_lshl_add_u64 v[186:187], v[186:187], 0, v[162:163]
	v_pk_mul_f32 v[180:181], v[16:17], s[100:101]
	v_pk_mul_f32 v[182:183], v[18:19], s[100:101]
	v_exp_f32_e32 v180, v180
	v_exp_f32_e32 v181, v181
	v_exp_f32_e32 v182, v182
	v_exp_f32_e32 v183, v183
	v_pk_add_f32 v[180:181], v[180:181], 1.0 op_sel_hi:[1,0]
	v_pk_add_f32 v[182:183], v[182:183], 1.0 op_sel_hi:[1,0]
	v_rcp_f32_e32 v180, v180
	v_rcp_f32_e32 v181, v181
	v_rcp_f32_e32 v182, v182
	v_rcp_f32_e32 v183, v183
	v_pk_mul_f32 v[180:181], v[16:17], v[180:181]
	v_pk_mul_f32 v[182:183], v[18:19], v[182:183]
	v_pk_mul_f32 v[180:181], v[180:181], v[12:13]
	v_pk_mul_f32 v[182:183], v[182:183], v[14:15]
	v_cvt_pk_bf16_f32 v12, v180, v181
	v_cvt_pk_bf16_f32 v13, v182, v183
	v_pk_mul_f32 v[180:181], v[8:9], s[100:101]
	v_pk_mul_f32 v[182:183], v[10:11], s[100:101]
	v_exp_f32_e32 v180, v180
	v_exp_f32_e32 v181, v181
	v_exp_f32_e32 v182, v182
	v_exp_f32_e32 v183, v183
	v_pk_add_f32 v[180:181], v[180:181], 1.0 op_sel_hi:[1,0]
	v_pk_add_f32 v[182:183], v[182:183], 1.0 op_sel_hi:[1,0]
	v_rcp_f32_e32 v180, v180
	v_rcp_f32_e32 v181, v181
	v_rcp_f32_e32 v182, v182
	v_rcp_f32_e32 v183, v183
	v_pk_mul_f32 v[180:181], v[8:9], v[180:181]
	v_pk_mul_f32 v[182:183], v[10:11], v[182:183]
	v_pk_mul_f32 v[180:181], v[180:181], v[4:5]
	v_pk_mul_f32 v[182:183], v[182:183], v[6:7]
	v_cvt_pk_bf16_f32 v14, v180, v181
	v_cvt_pk_bf16_f32 v15, v182, v183
	global_store_dwordx4 v[186:187], v[12:15], off nt
	s_andn2_b64 vcc, exec, s[42:43]
	s_cbranch_vccnz .LBB0_147
	s_andn2_b64 vcc, exec, s[2:3]
	s_cbranch_vccnz .LBB0_146
	s_barrier
	s_branch .LBB0_146

; #define PG8_LAS __attribute__((address_space(3)))
; __device__ __forceinline__ unsigned cvt_pk_bf16(float lo, float hi) { unsigned r; asm volatile("v_cvt_pk_bf16_f32 %0, %1, %2" : "=v"(r) : "v"(lo), "v"(hi)); return r; }
;     __device__ __forceinline__ void operator()(const f32x4 (&acc)[2][2][4][2], const Unit& u, int wr, int wc, int fr, int fq, PG8_LAS unsigned char*) const {
;         const int row0 = u.pm * BM + wr * 64 + fr, col0 = u.pn * BM + wc * 32 + 8 * fq;
; #pragma unroll
;         for (int ai = 0; ai < 2; ++ai)
; #pragma unroll
;         for (int mh = 0; mh < 2; ++mh) {
;             u32x4 r[2][2];
; #pragma unroll
;             for (int m2 = 0; m2 < 2; ++m2) { const size_t off = (size_t)(row0 + ai * HALF + (2 * mh + m2) * 16) * ldc + col0;
; #pragma unroll
;                 for (int bj = 0; bj < 2; ++bj) r[m2][bj] = *(const u32x4*)(xb + off + bj * HALF); }
; #pragma unroll
;             for (int m2 = 0; m2 < 2; ++m2) { const int m = 2 * mh + m2; const size_t off = (size_t)(row0 + ai * HALF + m * 16) * ldc + col0;
; #pragma unroll
;                 for (int bj = 0; bj < 2; ++bj) {
;                     const u32x4 q = r[m2][bj]; f32x4 o0, o1;
;                     o0[0] = __uint_as_float(q.x << 16); o0[1] = __uint_as_float(q.x & 0xffff0000u); o0[2] = __uint_as_float(q.y << 16); o0[3] = __uint_as_float(q.y & 0xffff0000u);
;                     o1[0] = __uint_as_float(q.z << 16); o1[1] = __uint_as_float(q.z & 0xffff0000u); o1[2] = __uint_as_float(q.w << 16); o1[3] = __uint_as_float(q.w & 0xffff0000u);
;                     o0 = o0 + acc[ai][bj][m][0] * scale; o1 = o1 + acc[ai][bj][m][1] * scale;
;                     u32x4 w; w.x = cvt_pk_bf16(o0[0], o0[1]); w.y = cvt_pk_bf16(o0[2], o0[3]); w.z = cvt_pk_bf16(o1[0], o1[1]); w.w = cvt_pk_bf16(o1[2], o1[3]);
;                     *(u32x4*)(xb + off + bj * HALF) = w; } }
;             asm volatile("" ::: "memory"); }
.LBB0_231:
	v_lshl_or_b32 v160, s49, 8, v178
	v_lshl_add_u32 v166, s48, 8, v176
	v_ashrrev_i32_e32 v161, 31, v160
	v_lshlrev_b64 v[160:161], 1, v[160:161]
	v_ashrrev_i32_e32 v167, 31, v166
	v_lshl_add_u64 v[162:163], s[98:99], 0, v[160:161]
	v_lshlrev_b64 v[164:165], 12, v[166:167]
	v_lshl_add_u64 v[184:185], v[162:163], 0, v[164:165]
	global_load_dwordx4 v[180:183], v[184:185], off
	s_nop 0
	global_load_dwordx4 v[184:187], v[184:185], off offset:256
	v_or_b32_e32 v188, 16, v166
	v_ashrrev_i32_e32 v189, 31, v188
	v_lshlrev_b64 v[196:197], 12, v[188:189]
	v_lshl_add_u64 v[192:193], v[162:163], 0, v[196:197]
	global_load_dwordx4 v[188:191], v[192:193], off
	s_nop 0
	global_load_dwordx4 v[192:195], v[192:193], off offset:256
	s_mov_b64 s[30:31], 0x80000
	s_and_b64 vcc, exec, s[44:45]
	s_waitcnt vmcnt(0)
	v_lshlrev_b32_e32 v198, 16, v180
	v_and_b32_e32 v199, 0xffff0000, v180
	v_lshlrev_b32_e32 v180, 16, v181
	v_and_b32_e32 v181, 0xffff0000, v181
	v_lshlrev_b32_e32 v200, 16, v182
	v_and_b32_e32 v201, 0xffff0000, v182
	v_lshlrev_b32_e32 v182, 16, v183
	v_and_b32_e32 v183, 0xffff0000, v183
	v_pk_fma_f32 v[128:129], v[128:129], 0.5, v[198:199] op_sel_hi:[1,0,1]
	v_pk_fma_f32 v[130:131], v[130:131], 0.5, v[180:181] op_sel_hi:[1,0,1]
	v_pk_fma_f32 v[180:181], v[126:127], 0.5, v[182:183] op_sel_hi:[1,0,1]
	v_pk_fma_f32 v[126:127], v[124:125], 0.5, v[200:201] op_sel_hi:[1,0,1]
	v_cvt_pk_bf16_f32 v124, v128, v129
	v_lshl_add_u64 v[128:129], s[98:99], 0, v[164:165]
	v_cvt_pk_bf16_f32 v125, v130, v131
	v_lshl_add_u64 v[128:129], v[128:129], 0, v[160:161]
	v_cvt_pk_bf16_f32 v126, v126, v127
	v_cvt_pk_bf16_f32 v127, v180, v181
	global_store_dwordx4 v[128:129], v[124:127], off nt
	v_lshlrev_b32_e32 v130, 16, v186
	v_and_b32_e32 v131, 0xffff0000, v186
	v_lshlrev_b32_e32 v124, 16, v184
	v_and_b32_e32 v125, 0xffff0000, v184
	v_lshlrev_b32_e32 v180, 16, v187
	v_and_b32_e32 v181, 0xffff0000, v187
	v_lshlrev_b32_e32 v126, 16, v185
	v_and_b32_e32 v127, 0xffff0000, v185
	v_pk_fma_f32 v[112:113], v[112:113], 0.5, v[124:125] op_sel_hi:[1,0,1]
	v_pk_fma_f32 v[124:125], v[110:111], 0.5, v[180:181] op_sel_hi:[1,0,1]
	v_pk_fma_f32 v[110:111], v[108:109], 0.5, v[130:131] op_sel_hi:[1,0,1]
	v_pk_fma_f32 v[114:115], v[114:115], 0.5, v[126:127] op_sel_hi:[1,0,1]
	v_cvt_pk_bf16_f32 v108, v112, v113
	v_lshlrev_b32_e32 v112, 16, v190
	v_cvt_pk_bf16_f32 v109, v114, v115
	v_cvt_pk_bf16_f32 v110, v110, v111
	v_cvt_pk_bf16_f32 v111, v124, v125
	global_store_dwordx4 v[128:129], v[108:111], off offset:256 nt
	v_and_b32_e32 v113, 0xffff0000, v190
	v_pk_fma_f32 v[112:113], v[116:117], 0.5, v[112:113] op_sel_hi:[1,0,1]
	v_lshlrev_b32_e32 v108, 16, v188
	v_and_b32_e32 v109, 0xffff0000, v188
	v_lshlrev_b32_e32 v110, 16, v189
	v_and_b32_e32 v111, 0xffff0000, v189
	v_pk_fma_f32 v[110:111], v[122:123], 0.5, v[110:111] op_sel_hi:[1,0,1]
	v_pk_fma_f32 v[108:109], v[120:121], 0.5, v[108:109] op_sel_hi:[1,0,1]
	v_lshlrev_b32_e32 v114, 16, v191
	v_and_b32_e32 v115, 0xffff0000, v191
	v_cvt_pk_bf16_f32 v108, v108, v109
	v_cvt_pk_bf16_f32 v109, v110, v111
	v_cvt_pk_bf16_f32 v110, v112, v113
	v_lshl_add_u64 v[112:113], s[98:99], 0, v[196:197]
	v_pk_fma_f32 v[114:115], v[118:119], 0.5, v[114:115] op_sel_hi:[1,0,1]
	v_lshl_add_u64 v[112:113], v[112:113], 0, v[160:161]
	v_cvt_pk_bf16_f32 v111, v114, v115
	global_store_dwordx4 v[112:113], v[108:111], off nt
	v_lshlrev_b32_e32 v114, 16, v194
	v_and_b32_e32 v115, 0xffff0000, v194
	v_lshlrev_b32_e32 v108, 16, v192
	v_and_b32_e32 v109, 0xffff0000, v192
	v_lshlrev_b32_e32 v116, 16, v195
	v_and_b32_e32 v117, 0xffff0000, v195
	v_lshlrev_b32_e32 v110, 16, v193
	v_and_b32_e32 v111, 0xffff0000, v193
	v_pk_fma_f32 v[104:105], v[104:105], 0.5, v[108:109] op_sel_hi:[1,0,1]
	v_pk_fma_f32 v[108:109], v[102:103], 0.5, v[116:117] op_sel_hi:[1,0,1]
	v_pk_fma_f32 v[102:103], v[100:101], 0.5, v[114:115] op_sel_hi:[1,0,1]
	v_cvt_pk_bf16_f32 v100, v104, v105
	v_pk_fma_f32 v[106:107], v[106:107], 0.5, v[110:111] op_sel_hi:[1,0,1]
	s_nop 0
	v_cvt_pk_bf16_f32 v101, v106, v107
	v_cvt_pk_bf16_f32 v102, v102, v103
	v_cvt_pk_bf16_f32 v103, v108, v109
	global_store_dwordx4 v[112:113], v[100:103], off offset:256 nt
	s_nop 1
	v_or_b32_e32 v100, 32, v166
	v_ashrrev_i32_e32 v101, 31, v100
	v_lshlrev_b64 v[100:101], 12, v[100:101]
	v_lshl_add_u64 v[102:103], v[162:163], 0, v[100:101]
	global_load_dwordx4 v[104:107], v[102:103], off
	global_load_dwordx4 v[108:111], v[102:103], off offset:256
	v_or_b32_e32 v102, 48, v166
	v_ashrrev_i32_e32 v103, 31, v102
	v_lshlrev_b64 v[102:103], 12, v[102:103]
	v_lshl_add_u64 v[116:117], v[162:163], 0, v[102:103]
	global_load_dwordx4 v[112:115], v[116:117], off
	s_nop 0
	global_load_dwordx4 v[116:119], v[116:117], off offset:256
	s_waitcnt vmcnt(3)
	v_lshlrev_b32_e32 v120, 16, v104
	v_and_b32_e32 v121, 0xffff0000, v104
	v_lshlrev_b32_e32 v104, 16, v105
	v_and_b32_e32 v105, 0xffff0000, v105
	v_lshlrev_b32_e32 v122, 16, v106
	v_and_b32_e32 v123, 0xffff0000, v106
	v_lshlrev_b32_e32 v106, 16, v107
	v_and_b32_e32 v107, 0xffff0000, v107
	v_pk_fma_f32 v[96:97], v[96:97], 0.5, v[120:121] op_sel_hi:[1,0,1]
	v_pk_fma_f32 v[98:99], v[98:99], 0.5, v[104:105] op_sel_hi:[1,0,1]
	v_pk_fma_f32 v[104:105], v[94:95], 0.5, v[106:107] op_sel_hi:[1,0,1]
	v_pk_fma_f32 v[94:95], v[92:93], 0.5, v[122:123] op_sel_hi:[1,0,1]
	v_cvt_pk_bf16_f32 v92, v96, v97
	v_lshl_add_u64 v[96:97], s[98:99], 0, v[100:101]
	v_cvt_pk_bf16_f32 v93, v98, v99
	v_lshl_add_u64 v[96:97], v[96:97], 0, v[160:161]
	v_cvt_pk_bf16_f32 v94, v94, v95
	v_cvt_pk_bf16_f32 v95, v104, v105
	global_store_dwordx4 v[96:97], v[92:95], off nt
	s_waitcnt vmcnt(3)
; __device__ __forceinline__ unsigned cvt_pk_bf16(float lo, float hi) { unsigned r; asm volatile("v_cvt_pk_bf16_f32 %0, %1, %2" : "=v"(r) : "v"(lo), "v"(hi)); return r; }
;     __device__ __forceinline__ void operator()(const f32x4 (&acc)[2][2][4][2], const Unit& u, int wr, int wc, int fr, int fq, PG8_LAS unsigned char*) const {
;     ...
; #pragma unroll
;             for (int m2 = 0; m2 < 2; ++m2) { const size_t off = (size_t)(row0 + ai * HALF + (2 * mh + m2) * 16) * ldc + col0;
; #pragma unroll
;                 for (int bj = 0; bj < 2; ++bj) r[m2][bj] = *(const u32x4*)(xb + off + bj * HALF); }
; #pragma unroll
;             for (int m2 = 0; m2 < 2; ++m2) { const int m = 2 * mh + m2; const size_t off = (size_t)(row0 + ai * HALF + m * 16) * ldc + col0;
; #pragma unroll
;                 for (int bj = 0; bj < 2; ++bj) {
;                     const u32x4 q = r[m2][bj]; f32x4 o0, o1;
;                     o0[0] = __uint_as_float(q.x << 16); o0[1] = __uint_as_float(q.x & 0xffff0000u); o0[2] = __uint_as_float(q.y << 16); o0[3] = __uint_as_float(q.y & 0xffff0000u);
;                     o1[0] = __uint_as_float(q.z << 16); o1[1] = __uint_as_float(q.z & 0xffff0000u); o1[2] = __uint_as_float(q.w << 16); o1[3] = __uint_as_float(q.w & 0xffff0000u);
;                     o0 = o0 + acc[ai][bj][m][0] * scale; o1 = o1 + acc[ai][bj][m][1] * scale;
;                     u32x4 w; w.x = cvt_pk_bf16(o0[0], o0[1]); w.y = cvt_pk_bf16(o0[2], o0[3]); w.z = cvt_pk_bf16(o1[0], o1[1]); w.w = cvt_pk_bf16(o1[2], o1[3]);
;                     *(u32x4*)(xb + off + bj * HALF) = w; } }
;             asm volatile("" ::: "memory"); }
	v_lshlrev_b32_e32 v98, 16, v110
	v_and_b32_e32 v99, 0xffff0000, v110
	v_lshlrev_b32_e32 v92, 16, v108
	v_and_b32_e32 v93, 0xffff0000, v108
	v_lshlrev_b32_e32 v100, 16, v111
	v_and_b32_e32 v101, 0xffff0000, v111
	v_lshlrev_b32_e32 v94, 16, v109
	v_and_b32_e32 v95, 0xffff0000, v109
	v_pk_fma_f32 v[80:81], v[80:81], 0.5, v[92:93] op_sel_hi:[1,0,1]
	v_pk_fma_f32 v[92:93], v[78:79], 0.5, v[100:101] op_sel_hi:[1,0,1]
	v_pk_fma_f32 v[78:79], v[76:77], 0.5, v[98:99] op_sel_hi:[1,0,1]
	v_pk_fma_f32 v[82:83], v[82:83], 0.5, v[94:95] op_sel_hi:[1,0,1]
	v_cvt_pk_bf16_f32 v76, v80, v81
	s_waitcnt vmcnt(2)
	v_lshlrev_b32_e32 v80, 16, v114
	v_cvt_pk_bf16_f32 v77, v82, v83
	v_cvt_pk_bf16_f32 v78, v78, v79
	v_cvt_pk_bf16_f32 v79, v92, v93
	global_store_dwordx4 v[96:97], v[76:79], off offset:256 nt
	v_and_b32_e32 v81, 0xffff0000, v114
	v_pk_fma_f32 v[80:81], v[84:85], 0.5, v[80:81] op_sel_hi:[1,0,1]
	v_lshlrev_b32_e32 v76, 16, v112
	v_and_b32_e32 v77, 0xffff0000, v112
	v_lshlrev_b32_e32 v78, 16, v113
	v_and_b32_e32 v79, 0xffff0000, v113
	v_pk_fma_f32 v[78:79], v[90:91], 0.5, v[78:79] op_sel_hi:[1,0,1]
	v_pk_fma_f32 v[76:77], v[88:89], 0.5, v[76:77] op_sel_hi:[1,0,1]
	v_lshlrev_b32_e32 v82, 16, v115
	v_and_b32_e32 v83, 0xffff0000, v115
	v_cvt_pk_bf16_f32 v76, v76, v77
	v_cvt_pk_bf16_f32 v77, v78, v79
	v_cvt_pk_bf16_f32 v78, v80, v81
	v_lshl_add_u64 v[80:81], s[98:99], 0, v[102:103]
	v_pk_fma_f32 v[82:83], v[86:87], 0.5, v[82:83] op_sel_hi:[1,0,1]
	v_lshl_add_u64 v[80:81], v[80:81], 0, v[160:161]
	v_cvt_pk_bf16_f32 v79, v82, v83
	global_store_dwordx4 v[80:81], v[76:79], off nt
	s_waitcnt vmcnt(3)
	v_lshlrev_b32_e32 v82, 16, v118
	v_and_b32_e32 v83, 0xffff0000, v118
	v_lshlrev_b32_e32 v76, 16, v116
	v_and_b32_e32 v77, 0xffff0000, v116
	v_lshlrev_b32_e32 v78, 16, v117
	v_and_b32_e32 v79, 0xffff0000, v117
	v_lshlrev_b32_e32 v84, 16, v119
	v_and_b32_e32 v85, 0xffff0000, v119
	v_pk_fma_f32 v[74:75], v[74:75], 0.5, v[78:79] op_sel_hi:[1,0,1]
	v_pk_fma_f32 v[72:73], v[72:73], 0.5, v[76:77] op_sel_hi:[1,0,1]
	v_pk_fma_f32 v[76:77], v[70:71], 0.5, v[84:85] op_sel_hi:[1,0,1]
	v_pk_fma_f32 v[70:71], v[68:69], 0.5, v[82:83] op_sel_hi:[1,0,1]
	v_cvt_pk_bf16_f32 v68, v72, v73
	v_cvt_pk_bf16_f32 v69, v74, v75
	s_nop 0
	v_cvt_pk_bf16_f32 v70, v70, v71
	v_cvt_pk_bf16_f32 v71, v76, v77
	global_store_dwordx4 v[80:81], v[68:71], off offset:256 nt
	s_nop 1
	v_lshl_add_u64 v[68:69], v[164:165], 0, s[30:31]
	v_lshl_add_u64 v[70:71], v[162:163], 0, v[68:69]
	global_load_dwordx4 v[72:75], v[70:71], off
	global_load_dwordx4 v[76:79], v[70:71], off offset:256
	s_mov_b64 s[30:31], 0x90000
	v_lshl_add_u64 v[70:71], v[164:165], 0, s[30:31]
	v_lshl_add_u64 v[84:85], v[162:163], 0, v[70:71]
	global_load_dwordx4 v[80:83], v[84:85], off
	s_nop 0
	global_load_dwordx4 v[84:87], v[84:85], off offset:256
	s_mov_b64 s[30:31], 0xa0000
	s_waitcnt vmcnt(3)
	v_lshlrev_b32_e32 v88, 16, v72
	v_and_b32_e32 v89, 0xffff0000, v72
	v_lshlrev_b32_e32 v72, 16, v73
	v_and_b32_e32 v73, 0xffff0000, v73
	v_lshlrev_b32_e32 v90, 16, v74
	v_and_b32_e32 v91, 0xffff0000, v74
	v_lshlrev_b32_e32 v74, 16, v75
	v_and_b32_e32 v75, 0xffff0000, v75
	v_pk_fma_f32 v[64:65], v[64:65], 0.5, v[88:89] op_sel_hi:[1,0,1]
	v_pk_fma_f32 v[66:67], v[66:67], 0.5, v[72:73] op_sel_hi:[1,0,1]
	v_pk_fma_f32 v[72:73], v[62:63], 0.5, v[74:75] op_sel_hi:[1,0,1]
	v_pk_fma_f32 v[62:63], v[60:61], 0.5, v[90:91] op_sel_hi:[1,0,1]
	v_cvt_pk_bf16_f32 v60, v64, v65
	v_lshl_add_u64 v[64:65], s[98:99], 0, v[68:69]
	v_cvt_pk_bf16_f32 v61, v66, v67
	v_lshl_add_u64 v[64:65], v[64:65], 0, v[160:161]
	v_cvt_pk_bf16_f32 v62, v62, v63
	v_cvt_pk_bf16_f32 v63, v72, v73
	global_store_dwordx4 v[64:65], v[60:63], off nt
	s_waitcnt vmcnt(3)
	v_lshlrev_b32_e32 v66, 16, v78
	v_and_b32_e32 v67, 0xffff0000, v78
	v_lshlrev_b32_e32 v60, 16, v76
	v_and_b32_e32 v61, 0xffff0000, v76
	v_lshlrev_b32_e32 v68, 16, v79
	v_and_b32_e32 v69, 0xffff0000, v79
	v_lshlrev_b32_e32 v62, 16, v77
	v_and_b32_e32 v63, 0xffff0000, v77
	v_pk_fma_f32 v[48:49], v[48:49], 0.5, v[60:61] op_sel_hi:[1,0,1]
	v_pk_fma_f32 v[60:61], v[46:47], 0.5, v[68:69] op_sel_hi:[1,0,1]
	v_pk_fma_f32 v[46:47], v[44:45], 0.5, v[66:67] op_sel_hi:[1,0,1]
	v_pk_fma_f32 v[50:51], v[50:51], 0.5, v[62:63] op_sel_hi:[1,0,1]
	v_cvt_pk_bf16_f32 v44, v48, v49
	s_waitcnt vmcnt(2)
	v_lshlrev_b32_e32 v48, 16, v82
	v_cvt_pk_bf16_f32 v45, v50, v51
	v_cvt_pk_bf16_f32 v46, v46, v47
	v_cvt_pk_bf16_f32 v47, v60, v61
	global_store_dwordx4 v[64:65], v[44:47], off offset:256 nt
	v_and_b32_e32 v49, 0xffff0000, v82
	v_pk_fma_f32 v[48:49], v[52:53], 0.5, v[48:49] op_sel_hi:[1,0,1]
	v_lshlrev_b32_e32 v44, 16, v80
	v_and_b32_e32 v45, 0xffff0000, v80
	v_lshlrev_b32_e32 v46, 16, v81
	v_and_b32_e32 v47, 0xffff0000, v81
	v_pk_fma_f32 v[46:47], v[58:59], 0.5, v[46:47] op_sel_hi:[1,0,1]
	v_pk_fma_f32 v[44:45], v[56:57], 0.5, v[44:45] op_sel_hi:[1,0,1]
	v_lshlrev_b32_e32 v50, 16, v83
	v_and_b32_e32 v51, 0xffff0000, v83
	v_cvt_pk_bf16_f32 v44, v44, v45
	v_cvt_pk_bf16_f32 v45, v46, v47
	v_cvt_pk_bf16_f32 v46, v48, v49
	v_lshl_add_u64 v[48:49], s[98:99], 0, v[70:71]
	v_pk_fma_f32 v[50:51], v[54:55], 0.5, v[50:51] op_sel_hi:[1,0,1]
	v_lshl_add_u64 v[48:49], v[48:49], 0, v[160:161]
	v_cvt_pk_bf16_f32 v47, v50, v51
	global_store_dwordx4 v[48:49], v[44:47], off nt
	s_waitcnt vmcnt(3)
; __device__ __forceinline__ unsigned cvt_pk_bf16(float lo, float hi) { unsigned r; asm volatile("v_cvt_pk_bf16_f32 %0, %1, %2" : "=v"(r) : "v"(lo), "v"(hi)); return r; }
;     __device__ __forceinline__ void operator()(const f32x4 (&acc)[2][2][4][2], const Unit& u, int wr, int wc, int fr, int fq, PG8_LAS unsigned char*) const {
;     ...
; #pragma unroll
;             for (int m2 = 0; m2 < 2; ++m2) { const size_t off = (size_t)(row0 + ai * HALF + (2 * mh + m2) * 16) * ldc + col0;
; #pragma unroll
;                 for (int bj = 0; bj < 2; ++bj) r[m2][bj] = *(const u32x4*)(xb + off + bj * HALF); }
; #pragma unroll
;             for (int m2 = 0; m2 < 2; ++m2) { const int m = 2 * mh + m2; const size_t off = (size_t)(row0 + ai * HALF + m * 16) * ldc + col0;
; #pragma unroll
;                 for (int bj = 0; bj < 2; ++bj) {
;                     const u32x4 q = r[m2][bj]; f32x4 o0, o1;
;                     o0[0] = __uint_as_float(q.x << 16); o0[1] = __uint_as_float(q.x & 0xffff0000u); o0[2] = __uint_as_float(q.y << 16); o0[3] = __uint_as_float(q.y & 0xffff0000u);
;                     o1[0] = __uint_as_float(q.z << 16); o1[1] = __uint_as_float(q.z & 0xffff0000u); o1[2] = __uint_as_float(q.w << 16); o1[3] = __uint_as_float(q.w & 0xffff0000u);
;                     o0 = o0 + acc[ai][bj][m][0] * scale; o1 = o1 + acc[ai][bj][m][1] * scale;
;                     u32x4 w; w.x = cvt_pk_bf16(o0[0], o0[1]); w.y = cvt_pk_bf16(o0[2], o0[3]); w.z = cvt_pk_bf16(o1[0], o1[1]); w.w = cvt_pk_bf16(o1[2], o1[3]);
;                     *(u32x4*)(xb + off + bj * HALF) = w; } }
;             asm volatile("" ::: "memory"); }
; template <class Epi, class Sched, bool ALIGN_EPI = false, bool SP2 = false>
; __device__ __forceinline__ void gemm_phase(PG8_LAS unsigned char* lds, const Gemm g, const Sched& S, const Epi& E) {
;     ...
;         if (!has_next) break;
	v_lshlrev_b32_e32 v50, 16, v86
	v_and_b32_e32 v51, 0xffff0000, v86
	v_lshlrev_b32_e32 v44, 16, v84
	v_and_b32_e32 v45, 0xffff0000, v84
	v_lshlrev_b32_e32 v52, 16, v87
	v_and_b32_e32 v53, 0xffff0000, v87
	v_lshlrev_b32_e32 v46, 16, v85
	v_and_b32_e32 v47, 0xffff0000, v85
	v_pk_fma_f32 v[40:41], v[40:41], 0.5, v[44:45] op_sel_hi:[1,0,1]
	v_pk_fma_f32 v[44:45], v[38:39], 0.5, v[52:53] op_sel_hi:[1,0,1]
	v_pk_fma_f32 v[38:39], v[36:37], 0.5, v[50:51] op_sel_hi:[1,0,1]
	v_pk_fma_f32 v[42:43], v[42:43], 0.5, v[46:47] op_sel_hi:[1,0,1]
	v_cvt_pk_bf16_f32 v36, v40, v41
	v_lshl_add_u64 v[40:41], v[164:165], 0, s[30:31]
	v_cvt_pk_bf16_f32 v37, v42, v43
	v_cvt_pk_bf16_f32 v38, v38, v39
	v_cvt_pk_bf16_f32 v39, v44, v45
	global_store_dwordx4 v[48:49], v[36:39], off offset:256 nt
	s_mov_b64 s[30:31], 0xb0000
	v_lshl_add_u64 v[42:43], v[164:165], 0, s[30:31]
	v_lshl_add_u64 v[36:37], v[162:163], 0, v[40:41]
	global_load_dwordx4 v[44:47], v[36:37], off
	global_load_dwordx4 v[48:51], v[36:37], off offset:256
	v_lshl_add_u64 v[36:37], v[162:163], 0, v[42:43]
	global_load_dwordx4 v[52:55], v[36:37], off
	s_nop 0
	global_load_dwordx4 v[36:39], v[36:37], off offset:256
	s_mov_b64 s[30:31], -1
	s_waitcnt vmcnt(3)
	v_lshlrev_b32_e32 v56, 16, v44
	v_and_b32_e32 v57, 0xffff0000, v44
	v_lshlrev_b32_e32 v44, 16, v45
	v_and_b32_e32 v45, 0xffff0000, v45
	v_lshlrev_b32_e32 v58, 16, v46
	v_and_b32_e32 v59, 0xffff0000, v46
	v_lshlrev_b32_e32 v46, 16, v47
	v_and_b32_e32 v47, 0xffff0000, v47
	v_pk_fma_f32 v[32:33], v[32:33], 0.5, v[56:57] op_sel_hi:[1,0,1]
	v_pk_fma_f32 v[34:35], v[34:35], 0.5, v[44:45] op_sel_hi:[1,0,1]
	v_pk_fma_f32 v[44:45], v[30:31], 0.5, v[46:47] op_sel_hi:[1,0,1]
	v_pk_fma_f32 v[30:31], v[28:29], 0.5, v[58:59] op_sel_hi:[1,0,1]
	v_cvt_pk_bf16_f32 v28, v32, v33
	v_lshl_add_u64 v[32:33], s[98:99], 0, v[40:41]
	v_cvt_pk_bf16_f32 v29, v34, v35
	v_lshl_add_u64 v[32:33], v[32:33], 0, v[160:161]
	v_cvt_pk_bf16_f32 v30, v30, v31
	v_cvt_pk_bf16_f32 v31, v44, v45
	global_store_dwordx4 v[32:33], v[28:31], off nt
	s_waitcnt vmcnt(3)
	v_lshlrev_b32_e32 v34, 16, v50
	v_and_b32_e32 v35, 0xffff0000, v50
	v_lshlrev_b32_e32 v28, 16, v48
	v_and_b32_e32 v29, 0xffff0000, v48
	v_lshlrev_b32_e32 v40, 16, v51
	v_and_b32_e32 v41, 0xffff0000, v51
	v_lshlrev_b32_e32 v30, 16, v49
	v_and_b32_e32 v31, 0xffff0000, v49
	v_pk_fma_f32 v[16:17], v[16:17], 0.5, v[28:29] op_sel_hi:[1,0,1]
	v_pk_fma_f32 v[28:29], v[14:15], 0.5, v[40:41] op_sel_hi:[1,0,1]
	v_pk_fma_f32 v[14:15], v[12:13], 0.5, v[34:35] op_sel_hi:[1,0,1]
	v_pk_fma_f32 v[18:19], v[18:19], 0.5, v[30:31] op_sel_hi:[1,0,1]
	v_cvt_pk_bf16_f32 v12, v16, v17
	s_waitcnt vmcnt(2)
	v_lshlrev_b32_e32 v16, 16, v54
	v_cvt_pk_bf16_f32 v13, v18, v19
	v_cvt_pk_bf16_f32 v14, v14, v15
	v_cvt_pk_bf16_f32 v15, v28, v29
	global_store_dwordx4 v[32:33], v[12:15], off offset:256 nt
	v_and_b32_e32 v17, 0xffff0000, v54
	v_pk_fma_f32 v[16:17], v[20:21], 0.5, v[16:17] op_sel_hi:[1,0,1]
	v_lshlrev_b32_e32 v12, 16, v52
	v_and_b32_e32 v13, 0xffff0000, v52
	v_lshlrev_b32_e32 v14, 16, v53
	v_and_b32_e32 v15, 0xffff0000, v53
	v_pk_fma_f32 v[14:15], v[26:27], 0.5, v[14:15] op_sel_hi:[1,0,1]
	v_pk_fma_f32 v[12:13], v[24:25], 0.5, v[12:13] op_sel_hi:[1,0,1]
	v_lshlrev_b32_e32 v18, 16, v55
	v_and_b32_e32 v19, 0xffff0000, v55
	v_cvt_pk_bf16_f32 v12, v12, v13
	v_cvt_pk_bf16_f32 v13, v14, v15
	v_cvt_pk_bf16_f32 v14, v16, v17
	v_lshl_add_u64 v[16:17], s[98:99], 0, v[42:43]
	v_pk_fma_f32 v[18:19], v[22:23], 0.5, v[18:19] op_sel_hi:[1,0,1]
	v_lshl_add_u64 v[16:17], v[16:17], 0, v[160:161]
	v_cvt_pk_bf16_f32 v15, v18, v19
	global_store_dwordx4 v[16:17], v[12:15], off nt
	s_waitcnt vmcnt(3)
	v_lshlrev_b32_e32 v18, 16, v38
	v_and_b32_e32 v19, 0xffff0000, v38
	v_lshlrev_b32_e32 v12, 16, v36
	v_and_b32_e32 v13, 0xffff0000, v36
	v_lshlrev_b32_e32 v20, 16, v39
	v_and_b32_e32 v21, 0xffff0000, v39
	v_lshlrev_b32_e32 v14, 16, v37
	v_and_b32_e32 v15, 0xffff0000, v37
	v_pk_fma_f32 v[8:9], v[8:9], 0.5, v[12:13] op_sel_hi:[1,0,1]
	v_pk_fma_f32 v[12:13], v[6:7], 0.5, v[20:21] op_sel_hi:[1,0,1]
	v_pk_fma_f32 v[6:7], v[4:5], 0.5, v[18:19] op_sel_hi:[1,0,1]
	v_pk_fma_f32 v[10:11], v[10:11], 0.5, v[14:15] op_sel_hi:[1,0,1]
	v_cvt_pk_bf16_f32 v4, v8, v9
	s_nop 0
	v_cvt_pk_bf16_f32 v5, v10, v11
	v_cvt_pk_bf16_f32 v6, v6, v7
	v_cvt_pk_bf16_f32 v7, v12, v13
	global_store_dwordx4 v[16:17], v[4:7], off offset:256 nt
	s_cbranch_vccnz .LBB0_216
	s_andn2_b64 vcc, exec, s[2:3]
	s_cbranch_vccnz .LBB0_215
	s_barrier
	s_branch .LBB0_215

; #define PG8_LAS __attribute__((address_space(3)))
; __device__ __forceinline__ unsigned cvt_pk_bf16(float lo, float hi) { unsigned r; asm volatile("v_cvt_pk_bf16_f32 %0, %1, %2" : "=v"(r) : "v"(lo), "v"(hi)); return r; }
;     __device__ __forceinline__ void operator()(const f32x4 (&acc)[2][2][4][2], const Unit& u, int wr, int wc, int fr, int fq, PG8_LAS unsigned char*) const {
;         const int row0 = u.pm * BM + wr * 64 + fr, col0 = u.pn * BM + wc * 32 + 8 * fq;
; #pragma unroll
;         for (int ai = 0; ai < 2; ++ai)
; #pragma unroll
;         for (int mh = 0; mh < 2; ++mh) {
;             u32x4 r[2][2];
; #pragma unroll
;             for (int m2 = 0; m2 < 2; ++m2) { const size_t off = (size_t)(row0 + ai * HALF + (2 * mh + m2) * 16) * ldc + col0;
; #pragma unroll
;                 for (int bj = 0; bj < 2; ++bj) r[m2][bj] = *(const u32x4*)(xb + off + bj * HALF); }
; #pragma unroll
;             for (int m2 = 0; m2 < 2; ++m2) { const int m = 2 * mh + m2; const size_t off = (size_t)(row0 + ai * HALF + m * 16) * ldc + col0;
; #pragma unroll
;                 for (int bj = 0; bj < 2; ++bj) {
;                     const u32x4 q = r[m2][bj]; f32x4 o0, o1;
;                     o0[0] = __uint_as_float(q.x << 16); o0[1] = __uint_as_float(q.x & 0xffff0000u); o0[2] = __uint_as_float(q.y << 16); o0[3] = __uint_as_float(q.y & 0xffff0000u);
;                     o1[0] = __uint_as_float(q.z << 16); o1[1] = __uint_as_float(q.z & 0xffff0000u); o1[2] = __uint_as_float(q.w << 16); o1[3] = __uint_as_float(q.w & 0xffff0000u);
;                     o0 = o0 + acc[ai][bj][m][0] * scale; o1 = o1 + acc[ai][bj][m][1] * scale;
;                     u32x4 w; w.x = cvt_pk_bf16(o0[0], o0[1]); w.y = cvt_pk_bf16(o0[2], o0[3]); w.z = cvt_pk_bf16(o1[0], o1[1]); w.w = cvt_pk_bf16(o1[2], o1[3]);
;                     *(u32x4*)(xb + off + bj * HALF) = w; } }
;             asm volatile("" ::: "memory"); }
.LBB0_634:
	v_lshl_or_b32 v160, s29, 8, v178
	v_lshl_add_u32 v166, s84, 8, v176
	v_ashrrev_i32_e32 v161, 31, v160
	v_lshlrev_b64 v[160:161], 1, v[160:161]
	v_ashrrev_i32_e32 v167, 31, v166
	v_lshl_add_u64 v[162:163], s[98:99], 0, v[160:161]
	v_lshlrev_b64 v[164:165], 12, v[166:167]
	v_lshl_add_u64 v[184:185], v[162:163], 0, v[164:165]
	global_load_dwordx4 v[180:183], v[184:185], off
	s_nop 0
	global_load_dwordx4 v[184:187], v[184:185], off offset:256
	v_or_b32_e32 v188, 16, v166
	v_ashrrev_i32_e32 v189, 31, v188
	v_lshlrev_b64 v[196:197], 12, v[188:189]
	v_lshl_add_u64 v[192:193], v[162:163], 0, v[196:197]
	global_load_dwordx4 v[188:191], v[192:193], off
	s_nop 0
	global_load_dwordx4 v[192:195], v[192:193], off offset:256
	s_mov_b64 s[38:39], 0x80000
	s_mov_b64 s[46:47], -1
	s_andn2_b64 vcc, exec, s[42:43]
	s_mov_b32 s97, 0xf800000
	s_waitcnt vmcnt(0)
	v_lshlrev_b32_e32 v198, 16, v180
	v_and_b32_e32 v199, 0xffff0000, v180
	v_lshlrev_b32_e32 v180, 16, v181
	v_and_b32_e32 v181, 0xffff0000, v181
	v_lshlrev_b32_e32 v200, 16, v182
	v_and_b32_e32 v201, 0xffff0000, v182
	v_lshlrev_b32_e32 v182, 16, v183
	v_and_b32_e32 v183, 0xffff0000, v183
	v_pk_add_f32 v[128:129], v[128:129], v[198:199]
	v_pk_add_f32 v[130:131], v[130:131], v[180:181]
	v_pk_add_f32 v[180:181], v[126:127], v[182:183]
	v_pk_add_f32 v[126:127], v[124:125], v[200:201]
	v_cvt_pk_bf16_f32 v124, v128, v129
	v_lshl_add_u64 v[128:129], s[98:99], 0, v[164:165]
	v_cvt_pk_bf16_f32 v125, v130, v131
	v_lshl_add_u64 v[128:129], v[128:129], 0, v[160:161]
	v_cvt_pk_bf16_f32 v126, v126, v127
	v_cvt_pk_bf16_f32 v127, v180, v181
	global_store_dwordx4 v[128:129], v[124:127], off nt
	v_lshlrev_b32_e32 v130, 16, v186
	v_and_b32_e32 v131, 0xffff0000, v186
	v_lshlrev_b32_e32 v124, 16, v184
	v_and_b32_e32 v125, 0xffff0000, v184
	v_lshlrev_b32_e32 v180, 16, v187
	v_and_b32_e32 v181, 0xffff0000, v187
	v_lshlrev_b32_e32 v126, 16, v185
	v_and_b32_e32 v127, 0xffff0000, v185
	v_pk_add_f32 v[112:113], v[112:113], v[124:125]
	v_pk_add_f32 v[124:125], v[110:111], v[180:181]
	v_pk_add_f32 v[110:111], v[108:109], v[130:131]
	v_pk_add_f32 v[114:115], v[114:115], v[126:127]
	v_cvt_pk_bf16_f32 v108, v112, v113
	v_lshlrev_b32_e32 v112, 16, v190
	v_cvt_pk_bf16_f32 v109, v114, v115
	v_cvt_pk_bf16_f32 v110, v110, v111
	v_cvt_pk_bf16_f32 v111, v124, v125
	global_store_dwordx4 v[128:129], v[108:111], off offset:256 nt
	v_and_b32_e32 v113, 0xffff0000, v190
	v_pk_add_f32 v[112:113], v[116:117], v[112:113]
	v_lshlrev_b32_e32 v108, 16, v188
	v_and_b32_e32 v109, 0xffff0000, v188
	v_lshlrev_b32_e32 v110, 16, v189
	v_and_b32_e32 v111, 0xffff0000, v189
	v_pk_add_f32 v[110:111], v[122:123], v[110:111]
	v_pk_add_f32 v[108:109], v[120:121], v[108:109]
	v_lshlrev_b32_e32 v114, 16, v191
	v_and_b32_e32 v115, 0xffff0000, v191
	v_cvt_pk_bf16_f32 v108, v108, v109
	v_cvt_pk_bf16_f32 v109, v110, v111
	v_cvt_pk_bf16_f32 v110, v112, v113
	v_lshl_add_u64 v[112:113], s[98:99], 0, v[196:197]
	v_pk_add_f32 v[114:115], v[118:119], v[114:115]
	v_lshl_add_u64 v[112:113], v[112:113], 0, v[160:161]
	v_cvt_pk_bf16_f32 v111, v114, v115
	global_store_dwordx4 v[112:113], v[108:111], off nt
	v_lshlrev_b32_e32 v114, 16, v194
	v_and_b32_e32 v115, 0xffff0000, v194
	v_lshlrev_b32_e32 v108, 16, v192
	v_and_b32_e32 v109, 0xffff0000, v192
	v_lshlrev_b32_e32 v116, 16, v195
	v_and_b32_e32 v117, 0xffff0000, v195
	v_lshlrev_b32_e32 v110, 16, v193
	v_and_b32_e32 v111, 0xffff0000, v193
	v_pk_add_f32 v[104:105], v[104:105], v[108:109]
	v_pk_add_f32 v[108:109], v[102:103], v[116:117]
	v_pk_add_f32 v[102:103], v[100:101], v[114:115]
	v_cvt_pk_bf16_f32 v100, v104, v105
	v_pk_add_f32 v[106:107], v[106:107], v[110:111]
	s_nop 0
	v_cvt_pk_bf16_f32 v101, v106, v107
	v_cvt_pk_bf16_f32 v102, v102, v103
	v_cvt_pk_bf16_f32 v103, v108, v109
	global_store_dwordx4 v[112:113], v[100:103], off offset:256 nt
	s_nop 1
	v_or_b32_e32 v100, 32, v166
	v_ashrrev_i32_e32 v101, 31, v100
	v_lshlrev_b64 v[100:101], 12, v[100:101]
	v_lshl_add_u64 v[102:103], v[162:163], 0, v[100:101]
	global_load_dwordx4 v[104:107], v[102:103], off
	global_load_dwordx4 v[108:111], v[102:103], off offset:256
	v_or_b32_e32 v102, 48, v166
	v_ashrrev_i32_e32 v103, 31, v102
	v_lshlrev_b64 v[102:103], 12, v[102:103]
	v_lshl_add_u64 v[116:117], v[162:163], 0, v[102:103]
	global_load_dwordx4 v[112:115], v[116:117], off
	s_nop 0
	global_load_dwordx4 v[116:119], v[116:117], off offset:256
	s_waitcnt vmcnt(3)
	v_lshlrev_b32_e32 v120, 16, v104
	v_and_b32_e32 v121, 0xffff0000, v104
	v_lshlrev_b32_e32 v104, 16, v105
	v_and_b32_e32 v105, 0xffff0000, v105
	v_lshlrev_b32_e32 v122, 16, v106
	v_and_b32_e32 v123, 0xffff0000, v106
	v_lshlrev_b32_e32 v106, 16, v107
	v_and_b32_e32 v107, 0xffff0000, v107
	v_pk_add_f32 v[96:97], v[96:97], v[120:121]
	v_pk_add_f32 v[98:99], v[98:99], v[104:105]
	v_pk_add_f32 v[104:105], v[94:95], v[106:107]
	v_pk_add_f32 v[94:95], v[92:93], v[122:123]
	v_cvt_pk_bf16_f32 v92, v96, v97
	v_lshl_add_u64 v[96:97], s[98:99], 0, v[100:101]
	v_cvt_pk_bf16_f32 v93, v98, v99
	v_lshl_add_u64 v[96:97], v[96:97], 0, v[160:161]
	v_cvt_pk_bf16_f32 v94, v94, v95
	v_cvt_pk_bf16_f32 v95, v104, v105
	global_store_dwordx4 v[96:97], v[92:95], off nt
	s_waitcnt vmcnt(3)
	v_lshlrev_b32_e32 v98, 16, v110
	v_and_b32_e32 v99, 0xffff0000, v110
	v_lshlrev_b32_e32 v92, 16, v108
	v_and_b32_e32 v93, 0xffff0000, v108
	v_lshlrev_b32_e32 v100, 16, v111
	v_and_b32_e32 v101, 0xffff0000, v111
	v_lshlrev_b32_e32 v94, 16, v109
	v_and_b32_e32 v95, 0xffff0000, v109
	v_pk_add_f32 v[80:81], v[80:81], v[92:93]
	v_pk_add_f32 v[92:93], v[78:79], v[100:101]
	v_pk_add_f32 v[78:79], v[76:77], v[98:99]
	v_pk_add_f32 v[82:83], v[82:83], v[94:95]
	v_cvt_pk_bf16_f32 v76, v80, v81
	s_waitcnt vmcnt(2)
; __device__ __forceinline__ unsigned cvt_pk_bf16(float lo, float hi) { unsigned r; asm volatile("v_cvt_pk_bf16_f32 %0, %1, %2" : "=v"(r) : "v"(lo), "v"(hi)); return r; }
;     __device__ __forceinline__ void operator()(const f32x4 (&acc)[2][2][4][2], const Unit& u, int wr, int wc, int fr, int fq, PG8_LAS unsigned char*) const {
;     ...
; #pragma unroll
;             for (int m2 = 0; m2 < 2; ++m2) { const size_t off = (size_t)(row0 + ai * HALF + (2 * mh + m2) * 16) * ldc + col0;
; #pragma unroll
;                 for (int bj = 0; bj < 2; ++bj) r[m2][bj] = *(const u32x4*)(xb + off + bj * HALF); }
; #pragma unroll
;             for (int m2 = 0; m2 < 2; ++m2) { const int m = 2 * mh + m2; const size_t off = (size_t)(row0 + ai * HALF + m * 16) * ldc + col0;
; #pragma unroll
;                 for (int bj = 0; bj < 2; ++bj) {
;                     const u32x4 q = r[m2][bj]; f32x4 o0, o1;
;                     o0[0] = __uint_as_float(q.x << 16); o0[1] = __uint_as_float(q.x & 0xffff0000u); o0[2] = __uint_as_float(q.y << 16); o0[3] = __uint_as_float(q.y & 0xffff0000u);
;                     o1[0] = __uint_as_float(q.z << 16); o1[1] = __uint_as_float(q.z & 0xffff0000u); o1[2] = __uint_as_float(q.w << 16); o1[3] = __uint_as_float(q.w & 0xffff0000u);
;                     o0 = o0 + acc[ai][bj][m][0] * scale; o1 = o1 + acc[ai][bj][m][1] * scale;
;                     u32x4 w; w.x = cvt_pk_bf16(o0[0], o0[1]); w.y = cvt_pk_bf16(o0[2], o0[3]); w.z = cvt_pk_bf16(o1[0], o1[1]); w.w = cvt_pk_bf16(o1[2], o1[3]);
;                     *(u32x4*)(xb + off + bj * HALF) = w; } }
;             asm volatile("" ::: "memory"); }
	v_lshlrev_b32_e32 v80, 16, v114
	v_cvt_pk_bf16_f32 v77, v82, v83
	v_cvt_pk_bf16_f32 v78, v78, v79
	v_cvt_pk_bf16_f32 v79, v92, v93
	global_store_dwordx4 v[96:97], v[76:79], off offset:256 nt
	v_and_b32_e32 v81, 0xffff0000, v114
	v_pk_add_f32 v[80:81], v[84:85], v[80:81]
	v_lshlrev_b32_e32 v76, 16, v112
	v_and_b32_e32 v77, 0xffff0000, v112
	v_lshlrev_b32_e32 v78, 16, v113
	v_and_b32_e32 v79, 0xffff0000, v113
	v_pk_add_f32 v[78:79], v[90:91], v[78:79]
	v_pk_add_f32 v[76:77], v[88:89], v[76:77]
	v_lshlrev_b32_e32 v82, 16, v115
	v_and_b32_e32 v83, 0xffff0000, v115
	v_cvt_pk_bf16_f32 v76, v76, v77
	v_cvt_pk_bf16_f32 v77, v78, v79
	v_cvt_pk_bf16_f32 v78, v80, v81
	v_lshl_add_u64 v[80:81], s[98:99], 0, v[102:103]
	v_pk_add_f32 v[82:83], v[86:87], v[82:83]
	v_lshl_add_u64 v[80:81], v[80:81], 0, v[160:161]
	v_cvt_pk_bf16_f32 v79, v82, v83
	global_store_dwordx4 v[80:81], v[76:79], off nt
	s_waitcnt vmcnt(3)
	v_lshlrev_b32_e32 v82, 16, v118
	v_and_b32_e32 v83, 0xffff0000, v118
	v_lshlrev_b32_e32 v76, 16, v116
	v_and_b32_e32 v77, 0xffff0000, v116
	v_lshlrev_b32_e32 v78, 16, v117
	v_and_b32_e32 v79, 0xffff0000, v117
	v_lshlrev_b32_e32 v84, 16, v119
	v_and_b32_e32 v85, 0xffff0000, v119
	v_pk_add_f32 v[74:75], v[74:75], v[78:79]
	v_pk_add_f32 v[72:73], v[72:73], v[76:77]
	v_pk_add_f32 v[76:77], v[70:71], v[84:85]
	v_pk_add_f32 v[70:71], v[68:69], v[82:83]
	v_cvt_pk_bf16_f32 v68, v72, v73
	v_cvt_pk_bf16_f32 v69, v74, v75
	s_nop 0
	v_cvt_pk_bf16_f32 v70, v70, v71
	v_cvt_pk_bf16_f32 v71, v76, v77
	global_store_dwordx4 v[80:81], v[68:71], off offset:256 nt
	s_nop 1
	v_lshl_add_u64 v[68:69], v[164:165], 0, s[38:39]
	v_lshl_add_u64 v[70:71], v[162:163], 0, v[68:69]
	global_load_dwordx4 v[72:75], v[70:71], off
	global_load_dwordx4 v[76:79], v[70:71], off offset:256
	s_mov_b64 s[38:39], 0x90000
	v_lshl_add_u64 v[70:71], v[164:165], 0, s[38:39]
	v_lshl_add_u64 v[84:85], v[162:163], 0, v[70:71]
	global_load_dwordx4 v[80:83], v[84:85], off
	s_nop 0
	global_load_dwordx4 v[84:87], v[84:85], off offset:256
	s_mov_b64 s[38:39], 0xa0000
	s_waitcnt vmcnt(3)
	v_lshlrev_b32_e32 v88, 16, v72
	v_and_b32_e32 v89, 0xffff0000, v72
	v_lshlrev_b32_e32 v72, 16, v73
	v_and_b32_e32 v73, 0xffff0000, v73
	v_lshlrev_b32_e32 v90, 16, v74
	v_and_b32_e32 v91, 0xffff0000, v74
	v_lshlrev_b32_e32 v74, 16, v75
	v_and_b32_e32 v75, 0xffff0000, v75
	v_pk_add_f32 v[64:65], v[64:65], v[88:89]
	v_pk_add_f32 v[66:67], v[66:67], v[72:73]
	v_pk_add_f32 v[72:73], v[62:63], v[74:75]
	v_pk_add_f32 v[62:63], v[60:61], v[90:91]
	v_cvt_pk_bf16_f32 v60, v64, v65
	v_lshl_add_u64 v[64:65], s[98:99], 0, v[68:69]
	v_cvt_pk_bf16_f32 v61, v66, v67
	v_lshl_add_u64 v[64:65], v[64:65], 0, v[160:161]
	v_cvt_pk_bf16_f32 v62, v62, v63
	v_cvt_pk_bf16_f32 v63, v72, v73
	global_store_dwordx4 v[64:65], v[60:63], off nt
	s_waitcnt vmcnt(3)
	v_lshlrev_b32_e32 v66, 16, v78
	v_and_b32_e32 v67, 0xffff0000, v78
	v_lshlrev_b32_e32 v60, 16, v76
	v_and_b32_e32 v61, 0xffff0000, v76
	v_lshlrev_b32_e32 v68, 16, v79
	v_and_b32_e32 v69, 0xffff0000, v79
	v_lshlrev_b32_e32 v62, 16, v77
	v_and_b32_e32 v63, 0xffff0000, v77
	v_pk_add_f32 v[48:49], v[48:49], v[60:61]
	v_pk_add_f32 v[60:61], v[46:47], v[68:69]
	v_pk_add_f32 v[46:47], v[44:45], v[66:67]
	v_pk_add_f32 v[50:51], v[50:51], v[62:63]
	v_cvt_pk_bf16_f32 v44, v48, v49
	s_waitcnt vmcnt(2)
	v_lshlrev_b32_e32 v48, 16, v82
	v_cvt_pk_bf16_f32 v45, v50, v51
	v_cvt_pk_bf16_f32 v46, v46, v47
	v_cvt_pk_bf16_f32 v47, v60, v61
	global_store_dwordx4 v[64:65], v[44:47], off offset:256 nt
	v_and_b32_e32 v49, 0xffff0000, v82
	v_pk_add_f32 v[48:49], v[52:53], v[48:49]
	v_lshlrev_b32_e32 v44, 16, v80
	v_and_b32_e32 v45, 0xffff0000, v80
	v_lshlrev_b32_e32 v46, 16, v81
	v_and_b32_e32 v47, 0xffff0000, v81
	v_pk_add_f32 v[46:47], v[58:59], v[46:47]
	v_pk_add_f32 v[44:45], v[56:57], v[44:45]
	v_lshlrev_b32_e32 v50, 16, v83
	v_and_b32_e32 v51, 0xffff0000, v83
	v_cvt_pk_bf16_f32 v44, v44, v45
	v_cvt_pk_bf16_f32 v45, v46, v47
	v_cvt_pk_bf16_f32 v46, v48, v49
	v_lshl_add_u64 v[48:49], s[98:99], 0, v[70:71]
	v_pk_add_f32 v[50:51], v[54:55], v[50:51]
	v_lshl_add_u64 v[48:49], v[48:49], 0, v[160:161]
	v_cvt_pk_bf16_f32 v47, v50, v51
	global_store_dwordx4 v[48:49], v[44:47], off nt
	s_waitcnt vmcnt(3)
; __device__ __forceinline__ unsigned cvt_pk_bf16(float lo, float hi) { unsigned r; asm volatile("v_cvt_pk_bf16_f32 %0, %1, %2" : "=v"(r) : "v"(lo), "v"(hi)); return r; }
;     __device__ __forceinline__ void operator()(const f32x4 (&acc)[2][2][4][2], const Unit& u, int wr, int wc, int fr, int fq, PG8_LAS unsigned char*) const {
;     ...
; #pragma unroll
;             for (int m2 = 0; m2 < 2; ++m2) { const size_t off = (size_t)(row0 + ai * HALF + (2 * mh + m2) * 16) * ldc + col0;
; #pragma unroll
;                 for (int bj = 0; bj < 2; ++bj) r[m2][bj] = *(const u32x4*)(xb + off + bj * HALF); }
; #pragma unroll
;             for (int m2 = 0; m2 < 2; ++m2) { const int m = 2 * mh + m2; const size_t off = (size_t)(row0 + ai * HALF + m * 16) * ldc + col0;
; #pragma unroll
;                 for (int bj = 0; bj < 2; ++bj) {
;                     const u32x4 q = r[m2][bj]; f32x4 o0, o1;
;                     o0[0] = __uint_as_float(q.x << 16); o0[1] = __uint_as_float(q.x & 0xffff0000u); o0[2] = __uint_as_float(q.y << 16); o0[3] = __uint_as_float(q.y & 0xffff0000u);
;                     o1[0] = __uint_as_float(q.z << 16); o1[1] = __uint_as_float(q.z & 0xffff0000u); o1[2] = __uint_as_float(q.w << 16); o1[3] = __uint_as_float(q.w & 0xffff0000u);
;                     o0 = o0 + acc[ai][bj][m][0] * scale; o1 = o1 + acc[ai][bj][m][1] * scale;
;                     u32x4 w; w.x = cvt_pk_bf16(o0[0], o0[1]); w.y = cvt_pk_bf16(o0[2], o0[3]); w.z = cvt_pk_bf16(o1[0], o1[1]); w.w = cvt_pk_bf16(o1[2], o1[3]);
;                     *(u32x4*)(xb + off + bj * HALF) = w; } }
;             asm volatile("" ::: "memory"); }
; template <class Epi, class Sched, bool ALIGN_EPI = false, bool SP2 = false>
; __device__ __forceinline__ void gemm_phase(PG8_LAS unsigned char* lds, const Gemm g, const Sched& S, const Epi& E) {
;     ...
;         if (!has_next) break;
	v_lshlrev_b32_e32 v50, 16, v86
	v_and_b32_e32 v51, 0xffff0000, v86
	v_lshlrev_b32_e32 v44, 16, v84
	v_and_b32_e32 v45, 0xffff0000, v84
	v_lshlrev_b32_e32 v52, 16, v87
	v_and_b32_e32 v53, 0xffff0000, v87
	v_lshlrev_b32_e32 v46, 16, v85
	v_and_b32_e32 v47, 0xffff0000, v85
	v_pk_add_f32 v[40:41], v[40:41], v[44:45]
	v_pk_add_f32 v[44:45], v[38:39], v[52:53]
	v_pk_add_f32 v[38:39], v[36:37], v[50:51]
	v_pk_add_f32 v[42:43], v[42:43], v[46:47]
	v_cvt_pk_bf16_f32 v36, v40, v41
	v_lshl_add_u64 v[40:41], v[164:165], 0, s[38:39]
	v_cvt_pk_bf16_f32 v37, v42, v43
	v_cvt_pk_bf16_f32 v38, v38, v39
	v_cvt_pk_bf16_f32 v39, v44, v45
	global_store_dwordx4 v[48:49], v[36:39], off offset:256 nt
	s_mov_b64 s[38:39], 0xb0000
	v_lshl_add_u64 v[42:43], v[164:165], 0, s[38:39]
	v_lshl_add_u64 v[36:37], v[162:163], 0, v[40:41]
	global_load_dwordx4 v[44:47], v[36:37], off
	global_load_dwordx4 v[48:51], v[36:37], off offset:256
	v_lshl_add_u64 v[36:37], v[162:163], 0, v[42:43]
	global_load_dwordx4 v[52:55], v[36:37], off
	s_nop 0
	global_load_dwordx4 v[36:39], v[36:37], off offset:256
	s_waitcnt vmcnt(3)
	v_lshlrev_b32_e32 v56, 16, v44
	v_and_b32_e32 v57, 0xffff0000, v44
	v_lshlrev_b32_e32 v44, 16, v45
	v_and_b32_e32 v45, 0xffff0000, v45
	v_lshlrev_b32_e32 v58, 16, v46
	v_and_b32_e32 v59, 0xffff0000, v46
	v_lshlrev_b32_e32 v46, 16, v47
	v_and_b32_e32 v47, 0xffff0000, v47
	v_pk_add_f32 v[32:33], v[32:33], v[56:57]
	v_pk_add_f32 v[34:35], v[34:35], v[44:45]
	v_pk_add_f32 v[44:45], v[30:31], v[46:47]
	v_pk_add_f32 v[30:31], v[28:29], v[58:59]
	v_cvt_pk_bf16_f32 v28, v32, v33
	v_lshl_add_u64 v[32:33], s[98:99], 0, v[40:41]
	v_cvt_pk_bf16_f32 v29, v34, v35
	v_lshl_add_u64 v[32:33], v[32:33], 0, v[160:161]
	v_cvt_pk_bf16_f32 v30, v30, v31
	v_cvt_pk_bf16_f32 v31, v44, v45
	global_store_dwordx4 v[32:33], v[28:31], off nt
	s_waitcnt vmcnt(3)
	v_lshlrev_b32_e32 v34, 16, v50
	v_and_b32_e32 v35, 0xffff0000, v50
	v_lshlrev_b32_e32 v28, 16, v48
	v_and_b32_e32 v29, 0xffff0000, v48
	v_lshlrev_b32_e32 v40, 16, v51
	v_and_b32_e32 v41, 0xffff0000, v51
	v_lshlrev_b32_e32 v30, 16, v49
	v_and_b32_e32 v31, 0xffff0000, v49
	v_pk_add_f32 v[16:17], v[16:17], v[28:29]
	v_pk_add_f32 v[28:29], v[14:15], v[40:41]
	v_pk_add_f32 v[14:15], v[12:13], v[34:35]
	v_pk_add_f32 v[18:19], v[18:19], v[30:31]
	v_cvt_pk_bf16_f32 v12, v16, v17
	s_waitcnt vmcnt(2)
	v_lshlrev_b32_e32 v16, 16, v54
	v_cvt_pk_bf16_f32 v13, v18, v19
	v_cvt_pk_bf16_f32 v14, v14, v15
	v_cvt_pk_bf16_f32 v15, v28, v29
	global_store_dwordx4 v[32:33], v[12:15], off offset:256 nt
	v_and_b32_e32 v17, 0xffff0000, v54
	v_pk_add_f32 v[16:17], v[20:21], v[16:17]
	v_lshlrev_b32_e32 v12, 16, v52
	v_and_b32_e32 v13, 0xffff0000, v52
	v_lshlrev_b32_e32 v14, 16, v53
	v_and_b32_e32 v15, 0xffff0000, v53
	v_pk_add_f32 v[14:15], v[26:27], v[14:15]
	v_pk_add_f32 v[12:13], v[24:25], v[12:13]
	v_lshlrev_b32_e32 v18, 16, v55
	v_and_b32_e32 v19, 0xffff0000, v55
	v_cvt_pk_bf16_f32 v12, v12, v13
	v_cvt_pk_bf16_f32 v13, v14, v15
	v_cvt_pk_bf16_f32 v14, v16, v17
	v_lshl_add_u64 v[16:17], s[98:99], 0, v[42:43]
	v_pk_add_f32 v[18:19], v[22:23], v[18:19]
	v_lshl_add_u64 v[16:17], v[16:17], 0, v[160:161]
	v_cvt_pk_bf16_f32 v15, v18, v19
	global_store_dwordx4 v[16:17], v[12:15], off nt
	s_waitcnt vmcnt(3)
	v_lshlrev_b32_e32 v18, 16, v38
	v_and_b32_e32 v19, 0xffff0000, v38
	v_lshlrev_b32_e32 v12, 16, v36
	v_and_b32_e32 v13, 0xffff0000, v36
	v_lshlrev_b32_e32 v20, 16, v39
	v_and_b32_e32 v21, 0xffff0000, v39
	v_lshlrev_b32_e32 v14, 16, v37
	v_and_b32_e32 v15, 0xffff0000, v37
	v_pk_add_f32 v[8:9], v[8:9], v[12:13]
	v_pk_add_f32 v[12:13], v[6:7], v[20:21]
	v_pk_add_f32 v[6:7], v[4:5], v[18:19]
	v_pk_add_f32 v[10:11], v[10:11], v[14:15]
	v_cvt_pk_bf16_f32 v4, v8, v9
	s_nop 0
	v_cvt_pk_bf16_f32 v5, v10, v11
	v_cvt_pk_bf16_f32 v6, v6, v7
	v_cvt_pk_bf16_f32 v7, v12, v13
	global_store_dwordx4 v[16:17], v[4:7], off offset:256 nt
	s_cbranch_vccnz .LBB0_623
	s_andn2_b64 vcc, exec, s[2:3]
	s_cbranch_vccnz .LBB0_622
	s_barrier
	s_branch .LBB0_622
